# P3 epilogue (EpiH) rewritten by hand: residual x loads of 8 row groups run 5 groups ahead in rotating register sets with counted vmcnt; global instead of flat ops (no rope change in this version)
# baseline (speedup 1.0000x reference)
; __device__ __forceinline__ unsigned cvtpk(float lo, float hi) { f32x2 v = {lo, hi}; bf16x2_t b = __builtin_convertvector(v, bf16x2_t); return __builtin_bit_cast(unsigned, b); }
;     __device__ __forceinline__ void operator()(const Acc& acc, const Unit& u, int wr, int wc, int fr, int fq) const {
;         asm volatile("" : "+v"(fr), "+v"(fq));
;         const int colbase = u.pn * 256 + wc * 64 + 8 * fq;
; #pragma unroll
;         for (int ai = 0; ai < 2; ++ai) {
;             f32x4 xv[4][2][2];
; #pragma unroll
;             for (int m = 0; m < 4; ++m) { const size_t off = (size_t)(u.pm * 256 + ai * 128 + wr * 64 + m * 16 + fr) * DM + colbase;
; #pragma unroll
;                 for (int bj = 0; bj < 2; ++bj) { xv[m][bj][0] = __builtin_nontemporal_load((const f32x4*)(x + off + 32 * bj)); xv[m][bj][1] = __builtin_nontemporal_load((const f32x4*)(x + off + 32 * bj + 4)); } }
; #pragma unroll
;             for (int m = 0; m < 4; ++m) {
;                 const int row = u.pm * 256 + ai * 128 + wr * 64 + m * 16 + fr;
;                 float ss = 0.f;
; #pragma unroll
;                 for (int bj = 0; bj < 2; ++bj) {
;                     const size_t off = (size_t)row * DM + colbase + 32 * bj;
;                     const f32x4 h0 = xv[m][bj][0] + acc[ai][bj][m][0], h1 = xv[m][bj][1] + acc[ai][bj][m][1];
;                     u32x4 w; w.x = cvtpk(h0.x, h0.y); w.y = cvtpk(h0.z, h0.w); w.z = cvtpk(h1.x, h1.y); w.w = cvtpk(h1.z, h1.w);
;                     *(u32x4*)(HB + off) = w;
;                     ss += (h0.x * h0.x + h0.y * h0.y) + (h0.z * h0.z + h0.w * h0.w) + (h1.x * h1.x + h1.y * h1.y) + (h1.z * h1.z + h1.w * h1.w);
;                 }
;                 ss = quad_sum(ss);
;                 if (fq == 0) atomicAdd(rowss + row, ss);
;             }
;         }
.LBB0_725:
	v_and_b32_e32 v192, 15, v200
	v_bfe_u32 v202, v200, 4, 2
	s_lshl_b32 s13, s22, 8
	s_or_b32 s13, s13, s86
	v_lshl_add_u32 v188, v202, 3, s13
	s_lshl_b32 s13, s20, 8
	s_add_i32 s13, s13, s79
	v_add_u32_e32 v192, s13, v192
	v_lshlrev_b32_e32 v190, 13, v192
	v_lshl_add_u32 v190, v188, 2, v190
	v_mov_b32_e32 v194, v190
	global_load_dwordx4 v[206:209], v194, s[8:9] nt
	global_load_dwordx4 v[210:213], v194, s[8:9] offset:16 nt
	global_load_dwordx4 v[214:217], v194, s[8:9] offset:128 nt
	global_load_dwordx4 v[218:221], v194, s[8:9] offset:144 nt
	v_add_u32_e32 v195, 0x20000, v190
	global_load_dwordx4 v[160:163], v195, s[8:9] nt
	global_load_dwordx4 v[164:167], v195, s[8:9] offset:16 nt
	global_load_dwordx4 v[168:171], v195, s[8:9] offset:128 nt
	global_load_dwordx4 v[172:175], v195, s[8:9] offset:144 nt
	v_add_u32_e32 v196, 0x40000, v190
	global_load_dwordx4 v[144:147], v196, s[8:9] nt
	global_load_dwordx4 v[148:151], v196, s[8:9] offset:16 nt
	global_load_dwordx4 v[152:155], v196, s[8:9] offset:128 nt
	global_load_dwordx4 v[156:159], v196, s[8:9] offset:144 nt
	v_add_u32_e32 v197, 0x60000, v190
	global_load_dwordx4 v[128:131], v197, s[8:9] nt
	global_load_dwordx4 v[132:135], v197, s[8:9] offset:16 nt
	global_load_dwordx4 v[136:139], v197, s[8:9] offset:128 nt
	global_load_dwordx4 v[140:143], v197, s[8:9] offset:144 nt
	v_add_u32_e32 v198, 0x100000, v190
	global_load_dwordx4 v[224:227], v198, s[8:9] nt
	global_load_dwordx4 v[228:231], v198, s[8:9] offset:16 nt
	global_load_dwordx4 v[232:235], v198, s[8:9] offset:128 nt
	global_load_dwordx4 v[236:239], v198, s[8:9] offset:144 nt
	v_lshlrev_b32_e32 v191, 12, v192
	v_lshl_add_u32 v191, v188, 1, v191
	v_lshlrev_b32_e32 v193, 2, v192
	v_cmp_eq_u32_e32 vcc, 0, v202
	v_mov_b32_e32 v222, v191
	v_mov_b32_e32 v199, v193
	s_waitcnt vmcnt(16)
	v_pk_add_f32 v[124:125], v[124:125], v[206:207]
	v_pk_add_f32 v[126:127], v[126:127], v[208:209]
	v_pk_add_f32 v[120:121], v[120:121], v[210:211]
	v_pk_add_f32 v[122:123], v[122:123], v[212:213]
	v_pk_add_f32 v[116:117], v[116:117], v[214:215]
	v_pk_add_f32 v[118:119], v[118:119], v[216:217]
	v_pk_add_f32 v[112:113], v[112:113], v[218:219]
	v_pk_add_f32 v[114:115], v[114:115], v[220:221]
	v_cvt_pk_bf16_f32 v206, v124, v125
	v_cvt_pk_bf16_f32 v207, v126, v127
	v_cvt_pk_bf16_f32 v208, v120, v121
	v_cvt_pk_bf16_f32 v209, v122, v123
	v_cvt_pk_bf16_f32 v210, v116, v117
	v_cvt_pk_bf16_f32 v211, v118, v119
	v_cvt_pk_bf16_f32 v212, v112, v113
	v_cvt_pk_bf16_f32 v213, v114, v115
	global_store_dwordx4 v222, v[206:209], s[10:11]
	global_store_dwordx4 v222, v[210:213], s[10:11] offset:64
	v_mul_f32_e32 v214, v124, v124
	v_fmac_f32_e32 v214, v125, v125
	v_fmac_f32_e32 v214, v126, v126
	v_fmac_f32_e32 v214, v127, v127
	v_mul_f32_e32 v215, v120, v120
	v_fmac_f32_e32 v215, v121, v121
	v_fmac_f32_e32 v215, v122, v122
	v_fmac_f32_e32 v215, v123, v123
	v_mul_f32_e32 v216, v116, v116
	v_fmac_f32_e32 v216, v117, v117
	v_fmac_f32_e32 v216, v118, v118
	v_fmac_f32_e32 v216, v119, v119
	v_mul_f32_e32 v217, v112, v112
	v_fmac_f32_e32 v217, v113, v113
	v_fmac_f32_e32 v217, v114, v114
	v_fmac_f32_e32 v217, v115, v115
	v_add_f32_e32 v214, v214, v215
	v_add_f32_e32 v216, v216, v217
	v_add_f32_e32 v214, v214, v216
	ds_swizzle_b32 v215, v214 offset:swizzle(SWAP,16)
	s_waitcnt lgkmcnt(0)
	v_add_f32_e32 v214, v214, v215
	v_mov_b32_e32 v215, v214
	s_nop 1
	v_permlane32_swap_b32_e32 v214, v215
	s_and_saveexec_b64 s[20:21], vcc
	s_nop 0
	v_add_f32_e32 v214, v214, v215
	global_atomic_add_f32 v199, v214, s[6:7]
	s_or_b64 exec, exec, s[20:21]
	v_add_u32_e32 v194, 0x120000, v190
	global_load_dwordx4 v[206:209], v194, s[8:9] nt
	global_load_dwordx4 v[210:213], v194, s[8:9] offset:16 nt
	global_load_dwordx4 v[214:217], v194, s[8:9] offset:128 nt
	global_load_dwordx4 v[218:221], v194, s[8:9] offset:144 nt
	v_add_u32_e32 v223, 0x10000, v191
	v_add_u32_e32 v189, 0x40, v193
	s_waitcnt vmcnt(19)
	v_pk_add_f32 v[108:109], v[108:109], v[160:161]
	v_pk_add_f32 v[110:111], v[110:111], v[162:163]
	v_pk_add_f32 v[104:105], v[104:105], v[164:165]
	v_pk_add_f32 v[106:107], v[106:107], v[166:167]
	v_pk_add_f32 v[100:101], v[100:101], v[168:169]
	v_pk_add_f32 v[102:103], v[102:103], v[170:171]
	v_pk_add_f32 v[96:97], v[96:97], v[172:173]
	v_pk_add_f32 v[98:99], v[98:99], v[174:175]
	v_cvt_pk_bf16_f32 v160, v108, v109
	v_cvt_pk_bf16_f32 v161, v110, v111
	v_cvt_pk_bf16_f32 v162, v104, v105
	v_cvt_pk_bf16_f32 v163, v106, v107
	v_cvt_pk_bf16_f32 v164, v100, v101
	v_cvt_pk_bf16_f32 v165, v102, v103
	v_cvt_pk_bf16_f32 v166, v96, v97
	v_cvt_pk_bf16_f32 v167, v98, v99
	global_store_dwordx4 v223, v[160:163], s[10:11]
	global_store_dwordx4 v223, v[164:167], s[10:11] offset:64
	v_mul_f32_e32 v168, v108, v108
	v_fmac_f32_e32 v168, v109, v109
	v_fmac_f32_e32 v168, v110, v110
	v_fmac_f32_e32 v168, v111, v111
	v_mul_f32_e32 v169, v104, v104
	v_fmac_f32_e32 v169, v105, v105
	v_fmac_f32_e32 v169, v106, v106
	v_fmac_f32_e32 v169, v107, v107
	v_mul_f32_e32 v170, v100, v100
	v_fmac_f32_e32 v170, v101, v101
	v_fmac_f32_e32 v170, v102, v102
	v_fmac_f32_e32 v170, v103, v103
	v_mul_f32_e32 v171, v96, v96
	v_fmac_f32_e32 v171, v97, v97
	v_fmac_f32_e32 v171, v98, v98
	v_fmac_f32_e32 v171, v99, v99
	v_add_f32_e32 v168, v168, v169
	v_add_f32_e32 v170, v170, v171
	v_add_f32_e32 v168, v168, v170
	ds_swizzle_b32 v169, v168 offset:swizzle(SWAP,16)
	s_waitcnt lgkmcnt(0)
; __device__ __forceinline__ unsigned cvtpk(float lo, float hi) { f32x2 v = {lo, hi}; bf16x2_t b = __builtin_convertvector(v, bf16x2_t); return __builtin_bit_cast(unsigned, b); }
;     __device__ __forceinline__ void operator()(const Acc& acc, const Unit& u, int wr, int wc, int fr, int fq) const {
;         asm volatile("" : "+v"(fr), "+v"(fq));
;         const int colbase = u.pn * 256 + wc * 64 + 8 * fq;
; #pragma unroll
;         for (int ai = 0; ai < 2; ++ai) {
;             f32x4 xv[4][2][2];
; #pragma unroll
;             for (int m = 0; m < 4; ++m) { const size_t off = (size_t)(u.pm * 256 + ai * 128 + wr * 64 + m * 16 + fr) * DM + colbase;
; #pragma unroll
;                 for (int bj = 0; bj < 2; ++bj) { xv[m][bj][0] = __builtin_nontemporal_load((const f32x4*)(x + off + 32 * bj)); xv[m][bj][1] = __builtin_nontemporal_load((const f32x4*)(x + off + 32 * bj + 4)); } }
; #pragma unroll
;             for (int m = 0; m < 4; ++m) {
;                 const int row = u.pm * 256 + ai * 128 + wr * 64 + m * 16 + fr;
;                 float ss = 0.f;
; #pragma unroll
;                 for (int bj = 0; bj < 2; ++bj) {
;                     const size_t off = (size_t)row * DM + colbase + 32 * bj;
;                     const f32x4 h0 = xv[m][bj][0] + acc[ai][bj][m][0], h1 = xv[m][bj][1] + acc[ai][bj][m][1];
;                     u32x4 w; w.x = cvtpk(h0.x, h0.y); w.y = cvtpk(h0.z, h0.w); w.z = cvtpk(h1.x, h1.y); w.w = cvtpk(h1.z, h1.w);
;                     *(u32x4*)(HB + off) = w;
;                     ss += (h0.x * h0.x + h0.y * h0.y) + (h0.z * h0.z + h0.w * h0.w) + (h1.x * h1.x + h1.y * h1.y) + (h1.z * h1.z + h1.w * h1.w);
;                 }
;                 ss = quad_sum(ss);
;                 if (fq == 0) atomicAdd(rowss + row, ss);
;             }
;         }
	v_add_f32_e32 v168, v168, v169
	v_mov_b32_e32 v169, v168
	s_nop 1
	v_permlane32_swap_b32_e32 v168, v169
	s_and_saveexec_b64 s[20:21], vcc
	s_nop 0
	v_add_f32_e32 v168, v168, v169
	global_atomic_add_f32 v189, v168, s[6:7]
	s_or_b64 exec, exec, s[20:21]
	v_add_u32_e32 v195, 0x140000, v190
	global_load_dwordx4 v[160:163], v195, s[8:9] nt
	global_load_dwordx4 v[164:167], v195, s[8:9] offset:16 nt
	global_load_dwordx4 v[168:171], v195, s[8:9] offset:128 nt
	global_load_dwordx4 v[172:175], v195, s[8:9] offset:144 nt
	v_add_u32_e32 v222, 0x20000, v191
	v_add_u32_e32 v199, 0x80, v193
	s_waitcnt vmcnt(22)
	v_pk_add_f32 v[92:93], v[92:93], v[144:145]
	v_pk_add_f32 v[94:95], v[94:95], v[146:147]
	v_pk_add_f32 v[88:89], v[88:89], v[148:149]
	v_pk_add_f32 v[90:91], v[90:91], v[150:151]
	v_pk_add_f32 v[84:85], v[84:85], v[152:153]
	v_pk_add_f32 v[86:87], v[86:87], v[154:155]
	v_pk_add_f32 v[80:81], v[80:81], v[156:157]
	v_pk_add_f32 v[82:83], v[82:83], v[158:159]
	v_cvt_pk_bf16_f32 v144, v92, v93
	v_cvt_pk_bf16_f32 v145, v94, v95
	v_cvt_pk_bf16_f32 v146, v88, v89
	v_cvt_pk_bf16_f32 v147, v90, v91
	v_cvt_pk_bf16_f32 v148, v84, v85
	v_cvt_pk_bf16_f32 v149, v86, v87
	v_cvt_pk_bf16_f32 v150, v80, v81
	v_cvt_pk_bf16_f32 v151, v82, v83
	global_store_dwordx4 v222, v[144:147], s[10:11]
	global_store_dwordx4 v222, v[148:151], s[10:11] offset:64
	v_mul_f32_e32 v152, v92, v92
	v_fmac_f32_e32 v152, v93, v93
	v_fmac_f32_e32 v152, v94, v94
	v_fmac_f32_e32 v152, v95, v95
	v_mul_f32_e32 v153, v88, v88
	v_fmac_f32_e32 v153, v89, v89
	v_fmac_f32_e32 v153, v90, v90
	v_fmac_f32_e32 v153, v91, v91
	v_mul_f32_e32 v154, v84, v84
	v_fmac_f32_e32 v154, v85, v85
	v_fmac_f32_e32 v154, v86, v86
	v_fmac_f32_e32 v154, v87, v87
	v_mul_f32_e32 v155, v80, v80
	v_fmac_f32_e32 v155, v81, v81
	v_fmac_f32_e32 v155, v82, v82
	v_fmac_f32_e32 v155, v83, v83
	v_add_f32_e32 v152, v152, v153
	v_add_f32_e32 v154, v154, v155
	v_add_f32_e32 v152, v152, v154
	ds_swizzle_b32 v153, v152 offset:swizzle(SWAP,16)
	s_waitcnt lgkmcnt(0)
	v_add_f32_e32 v152, v152, v153
	v_mov_b32_e32 v153, v152
	s_nop 1
	v_permlane32_swap_b32_e32 v152, v153
	s_and_saveexec_b64 s[20:21], vcc
	s_nop 0
	v_add_f32_e32 v152, v152, v153
	global_atomic_add_f32 v199, v152, s[6:7]
	s_or_b64 exec, exec, s[20:21]
	v_add_u32_e32 v196, 0x160000, v190
	global_load_dwordx4 v[144:147], v196, s[8:9] nt
	global_load_dwordx4 v[148:151], v196, s[8:9] offset:16 nt
	global_load_dwordx4 v[152:155], v196, s[8:9] offset:128 nt
	global_load_dwordx4 v[156:159], v196, s[8:9] offset:144 nt
	v_add_u32_e32 v223, 0x30000, v191
	v_add_u32_e32 v189, 0xc0, v193
	s_waitcnt vmcnt(25)
	v_pk_add_f32 v[76:77], v[76:77], v[128:129]
	v_pk_add_f32 v[78:79], v[78:79], v[130:131]
	v_pk_add_f32 v[72:73], v[72:73], v[132:133]
	v_pk_add_f32 v[74:75], v[74:75], v[134:135]
	v_pk_add_f32 v[68:69], v[68:69], v[136:137]
	v_pk_add_f32 v[70:71], v[70:71], v[138:139]
	v_pk_add_f32 v[64:65], v[64:65], v[140:141]
	v_pk_add_f32 v[66:67], v[66:67], v[142:143]
	v_cvt_pk_bf16_f32 v128, v76, v77
	v_cvt_pk_bf16_f32 v129, v78, v79
	v_cvt_pk_bf16_f32 v130, v72, v73
	v_cvt_pk_bf16_f32 v131, v74, v75
	v_cvt_pk_bf16_f32 v132, v68, v69
	v_cvt_pk_bf16_f32 v133, v70, v71
	v_cvt_pk_bf16_f32 v134, v64, v65
	v_cvt_pk_bf16_f32 v135, v66, v67
	global_store_dwordx4 v223, v[128:131], s[10:11]
	global_store_dwordx4 v223, v[132:135], s[10:11] offset:64
	v_mul_f32_e32 v136, v76, v76
	v_fmac_f32_e32 v136, v77, v77
	v_fmac_f32_e32 v136, v78, v78
	v_fmac_f32_e32 v136, v79, v79
	v_mul_f32_e32 v137, v72, v72
	v_fmac_f32_e32 v137, v73, v73
	v_fmac_f32_e32 v137, v74, v74
	v_fmac_f32_e32 v137, v75, v75
	v_mul_f32_e32 v138, v68, v68
	v_fmac_f32_e32 v138, v69, v69
	v_fmac_f32_e32 v138, v70, v70
	v_fmac_f32_e32 v138, v71, v71
	v_mul_f32_e32 v139, v64, v64
	v_fmac_f32_e32 v139, v65, v65
	v_fmac_f32_e32 v139, v66, v66
	v_fmac_f32_e32 v139, v67, v67
	v_add_f32_e32 v136, v136, v137
	v_add_f32_e32 v138, v138, v139
	v_add_f32_e32 v136, v136, v138
	ds_swizzle_b32 v137, v136 offset:swizzle(SWAP,16)
	s_waitcnt lgkmcnt(0)
	v_add_f32_e32 v136, v136, v137
	v_mov_b32_e32 v137, v136
	s_nop 1
	v_permlane32_swap_b32_e32 v136, v137
	s_and_saveexec_b64 s[20:21], vcc
	s_nop 0
	v_add_f32_e32 v136, v136, v137
	global_atomic_add_f32 v189, v136, s[6:7]
	s_or_b64 exec, exec, s[20:21]
	v_add_u32_e32 v222, 0x80000, v191
	v_add_u32_e32 v199, 0x200, v193
	s_waitcnt vmcnt(24)
	v_pk_add_f32 v[60:61], v[60:61], v[224:225]
	v_pk_add_f32 v[62:63], v[62:63], v[226:227]
	v_pk_add_f32 v[56:57], v[56:57], v[228:229]
	v_pk_add_f32 v[58:59], v[58:59], v[230:231]
	v_pk_add_f32 v[52:53], v[52:53], v[232:233]
	v_pk_add_f32 v[54:55], v[54:55], v[234:235]
	v_pk_add_f32 v[48:49], v[48:49], v[236:237]
	v_pk_add_f32 v[50:51], v[50:51], v[238:239]
	v_cvt_pk_bf16_f32 v224, v60, v61
	v_cvt_pk_bf16_f32 v225, v62, v63
	v_cvt_pk_bf16_f32 v226, v56, v57
	v_cvt_pk_bf16_f32 v227, v58, v59
	v_cvt_pk_bf16_f32 v228, v52, v53
	v_cvt_pk_bf16_f32 v229, v54, v55
	v_cvt_pk_bf16_f32 v230, v48, v49
	v_cvt_pk_bf16_f32 v231, v50, v51
	global_store_dwordx4 v222, v[224:227], s[10:11]
	global_store_dwordx4 v222, v[228:231], s[10:11] offset:64
	v_mul_f32_e32 v232, v60, v60
	v_fmac_f32_e32 v232, v61, v61
	v_fmac_f32_e32 v232, v62, v62
	v_fmac_f32_e32 v232, v63, v63
	v_mul_f32_e32 v233, v56, v56
	v_fmac_f32_e32 v233, v57, v57
	v_fmac_f32_e32 v233, v58, v58
	v_fmac_f32_e32 v233, v59, v59
	v_mul_f32_e32 v234, v52, v52
	v_fmac_f32_e32 v234, v53, v53
	v_fmac_f32_e32 v234, v54, v54
	v_fmac_f32_e32 v234, v55, v55
	v_mul_f32_e32 v235, v48, v48
	v_fmac_f32_e32 v235, v49, v49
	v_fmac_f32_e32 v235, v50, v50
	v_fmac_f32_e32 v235, v51, v51
	v_add_f32_e32 v232, v232, v233
	v_add_f32_e32 v234, v234, v235
	v_add_f32_e32 v232, v232, v234
	ds_swizzle_b32 v233, v232 offset:swizzle(SWAP,16)
	s_waitcnt lgkmcnt(0)
; __device__ __forceinline__ unsigned cvtpk(float lo, float hi) { f32x2 v = {lo, hi}; bf16x2_t b = __builtin_convertvector(v, bf16x2_t); return __builtin_bit_cast(unsigned, b); }
;     __device__ __forceinline__ void operator()(const Acc& acc, const Unit& u, int wr, int wc, int fr, int fq) const {
;         asm volatile("" : "+v"(fr), "+v"(fq));
;         const int colbase = u.pn * 256 + wc * 64 + 8 * fq;
; #pragma unroll
;         for (int ai = 0; ai < 2; ++ai) {
;             f32x4 xv[4][2][2];
; #pragma unroll
;             for (int m = 0; m < 4; ++m) { const size_t off = (size_t)(u.pm * 256 + ai * 128 + wr * 64 + m * 16 + fr) * DM + colbase;
; #pragma unroll
;                 for (int bj = 0; bj < 2; ++bj) { xv[m][bj][0] = __builtin_nontemporal_load((const f32x4*)(x + off + 32 * bj)); xv[m][bj][1] = __builtin_nontemporal_load((const f32x4*)(x + off + 32 * bj + 4)); } }
; #pragma unroll
;             for (int m = 0; m < 4; ++m) {
;                 const int row = u.pm * 256 + ai * 128 + wr * 64 + m * 16 + fr;
;                 float ss = 0.f;
; #pragma unroll
;                 for (int bj = 0; bj < 2; ++bj) {
;                     const size_t off = (size_t)row * DM + colbase + 32 * bj;
;                     const f32x4 h0 = xv[m][bj][0] + acc[ai][bj][m][0], h1 = xv[m][bj][1] + acc[ai][bj][m][1];
;                     u32x4 w; w.x = cvtpk(h0.x, h0.y); w.y = cvtpk(h0.z, h0.w); w.z = cvtpk(h1.x, h1.y); w.w = cvtpk(h1.z, h1.w);
;                     *(u32x4*)(HB + off) = w;
;                     ss += (h0.x * h0.x + h0.y * h0.y) + (h0.z * h0.z + h0.w * h0.w) + (h1.x * h1.x + h1.y * h1.y) + (h1.z * h1.z + h1.w * h1.w);
;                 }
;                 ss = quad_sum(ss);
;                 if (fq == 0) atomicAdd(rowss + row, ss);
;             }
;         }
	v_add_f32_e32 v232, v232, v233
	v_mov_b32_e32 v233, v232
	s_nop 1
	v_permlane32_swap_b32_e32 v232, v233
	s_and_saveexec_b64 s[20:21], vcc
	s_nop 0
	v_add_f32_e32 v232, v232, v233
	global_atomic_add_f32 v199, v232, s[6:7]
	s_or_b64 exec, exec, s[20:21]
	v_add_u32_e32 v223, 0x90000, v191
	v_add_u32_e32 v189, 0x240, v193
	s_waitcnt vmcnt(20)
	v_pk_add_f32 v[44:45], v[44:45], v[206:207]
	v_pk_add_f32 v[46:47], v[46:47], v[208:209]
	v_pk_add_f32 v[40:41], v[40:41], v[210:211]
	v_pk_add_f32 v[42:43], v[42:43], v[212:213]
	v_pk_add_f32 v[36:37], v[36:37], v[214:215]
	v_pk_add_f32 v[38:39], v[38:39], v[216:217]
	v_pk_add_f32 v[32:33], v[32:33], v[218:219]
	v_pk_add_f32 v[34:35], v[34:35], v[220:221]
	v_cvt_pk_bf16_f32 v206, v44, v45
	v_cvt_pk_bf16_f32 v207, v46, v47
	v_cvt_pk_bf16_f32 v208, v40, v41
	v_cvt_pk_bf16_f32 v209, v42, v43
	v_cvt_pk_bf16_f32 v210, v36, v37
	v_cvt_pk_bf16_f32 v211, v38, v39
	v_cvt_pk_bf16_f32 v212, v32, v33
	v_cvt_pk_bf16_f32 v213, v34, v35
	global_store_dwordx4 v223, v[206:209], s[10:11]
	global_store_dwordx4 v223, v[210:213], s[10:11] offset:64
	v_mul_f32_e32 v214, v44, v44
	v_fmac_f32_e32 v214, v45, v45
	v_fmac_f32_e32 v214, v46, v46
	v_fmac_f32_e32 v214, v47, v47
	v_mul_f32_e32 v215, v40, v40
	v_fmac_f32_e32 v215, v41, v41
	v_fmac_f32_e32 v215, v42, v42
	v_fmac_f32_e32 v215, v43, v43
	v_mul_f32_e32 v216, v36, v36
	v_fmac_f32_e32 v216, v37, v37
	v_fmac_f32_e32 v216, v38, v38
	v_fmac_f32_e32 v216, v39, v39
	v_mul_f32_e32 v217, v32, v32
	v_fmac_f32_e32 v217, v33, v33
	v_fmac_f32_e32 v217, v34, v34
	v_fmac_f32_e32 v217, v35, v35
	v_add_f32_e32 v214, v214, v215
	v_add_f32_e32 v216, v216, v217
	v_add_f32_e32 v214, v214, v216
	ds_swizzle_b32 v215, v214 offset:swizzle(SWAP,16)
	s_waitcnt lgkmcnt(0)
	v_add_f32_e32 v214, v214, v215
	v_mov_b32_e32 v215, v214
	s_nop 1
	v_permlane32_swap_b32_e32 v214, v215
	s_and_saveexec_b64 s[20:21], vcc
	s_nop 0
	v_add_f32_e32 v214, v214, v215
	global_atomic_add_f32 v189, v214, s[6:7]
	s_or_b64 exec, exec, s[20:21]
	v_add_u32_e32 v222, 0xa0000, v191
	v_add_u32_e32 v199, 0x280, v193
	s_waitcnt vmcnt(16)
	v_pk_add_f32 v[28:29], v[28:29], v[160:161]
	v_pk_add_f32 v[30:31], v[30:31], v[162:163]
	v_pk_add_f32 v[24:25], v[24:25], v[164:165]
	v_pk_add_f32 v[26:27], v[26:27], v[166:167]
	v_pk_add_f32 v[20:21], v[20:21], v[168:169]
	v_pk_add_f32 v[22:23], v[22:23], v[170:171]
	v_pk_add_f32 v[16:17], v[16:17], v[172:173]
	v_pk_add_f32 v[18:19], v[18:19], v[174:175]
	v_cvt_pk_bf16_f32 v160, v28, v29
	v_cvt_pk_bf16_f32 v161, v30, v31
	v_cvt_pk_bf16_f32 v162, v24, v25
	v_cvt_pk_bf16_f32 v163, v26, v27
	v_cvt_pk_bf16_f32 v164, v20, v21
	v_cvt_pk_bf16_f32 v165, v22, v23
	v_cvt_pk_bf16_f32 v166, v16, v17
	v_cvt_pk_bf16_f32 v167, v18, v19
	global_store_dwordx4 v222, v[160:163], s[10:11]
	global_store_dwordx4 v222, v[164:167], s[10:11] offset:64
	v_mul_f32_e32 v168, v28, v28
	v_fmac_f32_e32 v168, v29, v29
	v_fmac_f32_e32 v168, v30, v30
	v_fmac_f32_e32 v168, v31, v31
	v_mul_f32_e32 v169, v24, v24
	v_fmac_f32_e32 v169, v25, v25
	v_fmac_f32_e32 v169, v26, v26
	v_fmac_f32_e32 v169, v27, v27
	v_mul_f32_e32 v170, v20, v20
	v_fmac_f32_e32 v170, v21, v21
	v_fmac_f32_e32 v170, v22, v22
	v_fmac_f32_e32 v170, v23, v23
	v_mul_f32_e32 v171, v16, v16
	v_fmac_f32_e32 v171, v17, v17
	v_fmac_f32_e32 v171, v18, v18
	v_fmac_f32_e32 v171, v19, v19
	v_add_f32_e32 v168, v168, v169
	v_add_f32_e32 v170, v170, v171
	v_add_f32_e32 v168, v168, v170
	ds_swizzle_b32 v169, v168 offset:swizzle(SWAP,16)
	s_waitcnt lgkmcnt(0)
	v_add_f32_e32 v168, v168, v169
	v_mov_b32_e32 v169, v168
	s_nop 1
	v_permlane32_swap_b32_e32 v168, v169
	s_and_saveexec_b64 s[20:21], vcc
	s_nop 0
	v_add_f32_e32 v168, v168, v169
	global_atomic_add_f32 v199, v168, s[6:7]
	s_or_b64 exec, exec, s[20:21]
	v_add_u32_e32 v223, 0xb0000, v191
	v_add_u32_e32 v189, 0x2c0, v193
	s_waitcnt vmcnt(12)
	v_pk_add_f32 v[12:13], v[12:13], v[144:145]
	v_pk_add_f32 v[14:15], v[14:15], v[146:147]
	v_pk_add_f32 v[8:9], v[8:9], v[148:149]
	v_pk_add_f32 v[10:11], v[10:11], v[150:151]
	v_pk_add_f32 v[4:5], v[4:5], v[152:153]
	v_pk_add_f32 v[6:7], v[6:7], v[154:155]
	v_pk_add_f32 v[0:1], v[0:1], v[156:157]
	v_pk_add_f32 v[2:3], v[2:3], v[158:159]
	v_cvt_pk_bf16_f32 v144, v12, v13
	v_cvt_pk_bf16_f32 v145, v14, v15
	v_cvt_pk_bf16_f32 v146, v8, v9
	v_cvt_pk_bf16_f32 v147, v10, v11
	v_cvt_pk_bf16_f32 v148, v4, v5
	v_cvt_pk_bf16_f32 v149, v6, v7
	v_cvt_pk_bf16_f32 v150, v0, v1
	v_cvt_pk_bf16_f32 v151, v2, v3
	global_store_dwordx4 v223, v[144:147], s[10:11]
	global_store_dwordx4 v223, v[148:151], s[10:11] offset:64
	v_mul_f32_e32 v152, v12, v12
	v_fmac_f32_e32 v152, v13, v13
	v_fmac_f32_e32 v152, v14, v14
	v_fmac_f32_e32 v152, v15, v15
	v_mul_f32_e32 v153, v8, v8
	v_fmac_f32_e32 v153, v9, v9
	v_fmac_f32_e32 v153, v10, v10
	v_fmac_f32_e32 v153, v11, v11
	v_mul_f32_e32 v154, v4, v4
	v_fmac_f32_e32 v154, v5, v5
	v_fmac_f32_e32 v154, v6, v6
	v_fmac_f32_e32 v154, v7, v7
	v_mul_f32_e32 v155, v0, v0
	v_fmac_f32_e32 v155, v1, v1
	v_fmac_f32_e32 v155, v2, v2
	v_fmac_f32_e32 v155, v3, v3
	v_add_f32_e32 v152, v152, v153
	v_add_f32_e32 v154, v154, v155
	v_add_f32_e32 v152, v152, v154
	ds_swizzle_b32 v153, v152 offset:swizzle(SWAP,16)
	s_waitcnt lgkmcnt(0)
	v_add_f32_e32 v152, v152, v153
	v_mov_b32_e32 v153, v152
	s_nop 1
	v_permlane32_swap_b32_e32 v152, v153
	s_and_saveexec_b64 s[20:21], vcc
	s_nop 0
	v_add_f32_e32 v152, v152, v153
	global_atomic_add_f32 v189, v152, s[6:7]
	s_or_b64 exec, exec, s[20:21]
	s_andn2_b64 vcc, exec, s[4:5]
	s_mov_b64 s[4:5], -1
	s_cbranch_vccnz .LBB0_714
	s_and_b64 vcc, exec, s[0:1]
	s_cbranch_vccnz .LBB0_713
	s_barrier
	s_branch .LBB0_713
